# p128 operand loads batched 4-deep with scalar trip count; QK epilogue t%S and xL via bfe/shift (power-of-two sequence lengths) instead of magic-number division
# speedup vs baseline: 1.0010x; 1.0001x over previous
; __device__ __forceinline__ unsigned cvt_pk_bf16(float lo, float hi) { unsigned r; asm("v_cvt_pk_bf16_f32 %0, %1, %2" : "=v"(r) : "v"(lo), "v"(hi)); return r; }
; __device__ __forceinline__ float rinv_of(unsigned long long ss) { return rsqrtf((float)ss * (1.f / 16777216.f) * (1.f / DM) + 1e-6f); }
;   __device__ __forceinline__ void operator()(const f32x4 (&acc)[2][2][4][2], const Unit& u, const EpiCtx& x_, int wr, int wc, int fr, int fq) const {
;     ...
;     const int g = (hq % 48) >> 4, lg = 2 * g, L = S >> lg;
;     const bool isq = hq < 48; const int hh = isq ? hq : hq - 48;
;     bf16_t* obase = (bf16_t*)(isq ? u.C : x_.C2) + (size_t)hh * TS * 128 + wh * 64 + 8 * fq;
;     const float* gbase = (const float*)(isq ? x_.aux : x_.aux2) + wh * 64 + 8 * fq;
; #pragma unroll
;     for (int ai = 0; ai < 2; ++ai)
; #pragma unroll
;       for (int m = 0; m < 4; ++m) {
;         const int t = u.r0 + ai * 128 + wr * 64 + m * 16 + fr;
;         const int seq = t / S, n = t % S, pos = seq * S + (n & ((1 << lg) - 1)) * L + (n >> lg);
;         const float rs = rinv_of(ssv[ai][m]);
;         const float* rp = (const float*)0; (void)rp;
;         const float r0 = red[((wr * 2 + hd) * 128 + ai * 64 + m * 16 + fr) * 2], r1 = red[((wr * 2 + hd) * 128 + ai * 64 + m * 16 + fr) * 2 + 1];
;         const float rinv = rs * rsqrtf((r0 + r1) * (rs * rs) * (1.f / 128.f) + 1e-6f);
; #pragma unroll
;         for (int bj = 0; bj < 2; ++bj) {
;           const f32x4 g0 = *(const f32x4*)(gbase + bj * 32), g1 = *(const f32x4*)(gbase + bj * 32 + 4);
;           const f32x4 v0 = acc[ai][bj][m][0] * rinv * g0, v1 = acc[ai][bj][m][1] * rinv * g1;
;           uint4 o; o.x = cvt_pk_bf16(v0[0], v0[1]); o.y = cvt_pk_bf16(v0[2], v0[3]); o.z = cvt_pk_bf16(v1[0], v1[1]); o.w = cvt_pk_bf16(v1[2], v1[3]);
;           *(uint4*)(obase + (size_t)pos * 128 + bj * 32) = o;
;         }
.LBB0_587:
	s_or_b64 exec, exec, s[2:3]
	s_ashr_i32 s1, s1, 7
	s_add_i32 s1, s1, s86
	s_mul_hi_i32 s2, s1, 0x2aaaaaab
	s_lshr_b32 s3, s2, 31
	s_lshr_b32 s2, s2, 3
	s_add_i32 s2, s2, s3
	s_mul_i32 s2, s2, 48
	s_sub_i32 s2, s1, s2
	s_ashr_i32 s2, s2, 3
	s_and_b32 s39, s2, -2
	s_lshr_b32 s42, s17, s39
	s_cmp_lt_i32 s1, 48
	s_cselect_b64 s[2:3], -1, 0
	s_sub_i32 s30, s1, 48
	s_and_b64 s[28:29], s[2:3], exec
	s_cselect_b32 s28, s1, s30
	s_cselect_b32 s1, s5, s87
	s_cselect_b32 s30, s4, s83
	s_ashr_i32 s29, s28, 31
	s_lshl_b64 s[4:5], s[28:29], 22
	s_add_u32 s4, s30, s4
	s_addc_u32 s1, s1, s5
	s_lshl_b32 s5, s61, 1
	s_add_u32 s4, s4, s5
	s_addc_u32 s5, s1, 0
	s_and_b64 s[2:3], s[2:3], exec
	s_cselect_b32 s2, s19, s47
	s_cselect_b32 s1, s18, s46
	s_add_u32 s2, s2, s84
	s_addc_u32 s1, s1, s85
	s_lshl_b32 s3, s61, 2
	v_lshlrev_b32_e32 v80, 1, v138
	s_add_u32 s2, s2, s3
	v_lshl_add_u64 v[146:147], s[4:5], 0, v[80:81]
	s_addc_u32 s3, s1, 0
	v_lshlrev_b32_e32 v80, 2, v138
	v_lshl_add_u64 v[142:143], s[2:3], 0, v[80:81]
	s_nop 1
	global_load_dwordx4 v[190:193], v[142:143], off
	global_load_dwordx4 v[194:197], v[142:143], off offset:16
	global_load_dwordx4 v[198:201], v[142:143], off offset:128
	global_load_dwordx4 v[202:205], v[142:143], off offset:144
	v_sub_u32_e32 v80, 0, v140
	v_max_i32_e32 v80, v140, v80
	v_mul_hi_u32 v130, v80, v172
	v_mul_lo_u32 v130, v130, s17
	v_sub_u32_e32 v80, v80, v130
	v_cmp_le_u32_e64 s[2:3], s17, v80
	v_subrev_u32_e32 v130, s17, v80
	s_lshl_b32 s43, -1, s39
	v_cndmask_b32_e64 v80, v80, v130, s[2:3]
	v_cmp_le_u32_e64 s[2:3], s17, v80
	v_subrev_u32_e32 v130, s17, v80
	s_waitcnt lgkmcnt(0)
	s_barrier
	v_cndmask_b32_e64 v80, v80, v130, s[2:3]
	v_xor_b32_e32 v80, v80, v141
	v_sub_u32_e32 v80, v80, v141
	v_bitop3_b32 v130, v80, s43, v80 bitop3:0x30
	v_mul_lo_u32 v130, v130, s42
	s_waitcnt lgkmcnt(0)
	v_ashrrev_i32_e32 v131, s39, v80
	v_sub_u32_e32 v80, v140, v80
	v_add3_u32 v130, v80, v131, v130
	s_waitcnt vmcnt(0)
	v_ffbh_u32_e32 v80, v133
	v_min_u32_e32 v80, 32, v80
	v_lshlrev_b64 v[132:133], v80, v[132:133]
	v_min_u32_e32 v131, 1, v132
	v_or_b32_e32 v131, v133, v131
	v_cvt_f32_u32_e32 v131, v131
	v_sub_u32_e32 v80, 32, v80
	v_add_u32_e32 v178, s0, v169
	v_ldexp_f32 v80, v131, v80
	v_mul_f32_e32 v80, 0x33800000, v80
	v_fmamk_f32 v80, v80, 0x3a000000, v234
	v_cmp_gt_f32_e64 s[2:3], s50, v80
	v_mul_f32_e32 v131, 0x4b800000, v80
	s_cmp_eq_u32 s75, s79
	v_cndmask_b32_e64 v80, v80, v131, s[2:3]
	v_rsq_f32_e32 v80, v80
	s_mov_b32 s1, s44
	v_mul_f32_e32 v131, 0x45800000, v80
	v_cndmask_b32_e64 v141, v80, v131, s[2:3]
	v_add_u32_e32 v80, 0, v168
	v_add_u32_e32 v80, 0x20800, v80
	ds_read_b64 v[132:133], v80
	v_ashrrev_i32_e32 v131, 31, v130
	v_lshlrev_b64 v[130:131], 8, v[130:131]
	v_lshl_add_u64 v[160:161], v[146:147], 0, v[130:131]
	v_mul_f32_e32 v177, v141, v141
	s_waitcnt lgkmcnt(0)
	v_pk_add_f32 v[174:175], v[132:133], v[132:133] op_sel_hi:[0,1]
	s_nop 0
	s_nop 0
	v_ffbh_u32_e32 v174, v151
	v_min_u32_e32 v174, 32, v174
	v_lshlrev_b64 v[150:151], v174, v[150:151]
	v_min_u32_e32 v150, 1, v150
	v_or_b32_e32 v150, v151, v150
	v_cvt_f32_u32_e32 v150, v150
	v_sub_u32_e32 v151, 32, v174
	v_mov_b32_e32 v181, v175
	v_ldexp_f32 v176, v150, v151
	v_pk_mul_f32 v[174:175], v[176:177], v[180:181]
	v_mov_b64_e32 v[150:151], s[62:63]
	v_pk_fma_f32 v[174:175], v[174:175], s[26:27], v[150:151] op_sel_hi:[1,1,0]
	s_nop 0
	v_mul_f32_e32 v176, 0x4b800000, v175
	v_cmp_gt_f32_e64 s[4:5], s50, v175
	v_cmp_gt_f32_e64 s[2:3], s50, v174
	s_nop 0
	v_cndmask_b32_e64 v175, v175, v176, s[4:5]
	v_rsq_f32_e32 v175, v175
	s_nop 0
	v_mul_f32_e32 v176, 0x45800000, v175
	v_cndmask_b32_e64 v175, v175, v176, s[4:5]
	v_mul_f32_e32 v176, v141, v175
	v_pk_mul_f32 v[122:123], v[122:123], v[176:177] op_sel_hi:[1,0]
	v_pk_mul_f32 v[124:125], v[124:125], v[176:177] op_sel_hi:[1,0]
	v_pk_mul_f32 v[126:127], v[126:127], v[176:177] op_sel_hi:[1,0]
	v_pk_mul_f32 v[128:129], v[128:129], v[176:177] op_sel_hi:[1,0]
	v_pk_mul_f32 v[118:119], v[118:119], v[176:177] op_sel_hi:[1,0]
	v_pk_mul_f32 v[120:121], v[120:121], v[176:177] op_sel_hi:[1,0]
	v_pk_mul_f32 v[114:115], v[114:115], v[176:177] op_sel_hi:[1,0]
	v_pk_mul_f32 v[116:117], v[116:117], v[176:177] op_sel_hi:[1,0]
	s_waitcnt lgkmcnt(0)
	v_pk_mul_f32 v[128:129], v[192:193], v[128:129]
	v_pk_mul_f32 v[132:133], v[196:197], v[124:125]
	v_pk_mul_f32 v[124:125], v[194:195], v[122:123]
	v_pk_mul_f32 v[126:127], v[190:191], v[126:127]
	v_cvt_pk_bf16_f32 v123, v128, v129
	v_cvt_pk_bf16_f32 v124, v124, v125
	v_cvt_pk_bf16_f32 v125, v132, v133
	v_add_u32_e32 v131, s0, v170
	v_cvt_pk_bf16_f32 v122, v126, v127
	global_store_dwordx4 v[160:161], v[122:125], off
	s_nop 0
	s_nop 0
	s_nop 0
	s_waitcnt lgkmcnt(0)
	v_pk_mul_f32 v[120:121], v[200:201], v[120:121]
	v_pk_mul_f32 v[118:119], v[198:199], v[118:119]
	v_pk_mul_f32 v[122:123], v[204:205], v[116:117]
	v_pk_mul_f32 v[116:117], v[202:203], v[114:115]
	v_cvt_pk_bf16_f32 v115, v120, v121
	v_cvt_pk_bf16_f32 v114, v118, v119
	s_nop 0
	v_cvt_pk_bf16_f32 v116, v116, v117
	v_cvt_pk_bf16_f32 v117, v122, v123
	global_store_dwordx4 v[160:161], v[114:117], off offset:64
	s_nop 1
	s_ff1_i32_b32 s101, s17
	s_ff1_i32_b32 s100, s42
	v_bfe_u32 v114, v178, 0, s101
	v_bitop3_b32 v115, v114, s43, v114 bitop3:0x30
	v_lshlrev_b32_e32 v115, s100, v115
	v_ashrrev_i32_e32 v116, s39, v114
	v_sub_u32_e32 v114, v178, v114
	v_add3_u32 v114, v114, v116, v115
	v_mul_f32_e32 v115, 0x4b800000, v174
	v_cndmask_b32_e64 v115, v174, v115, s[2:3]
	v_rsq_f32_e32 v115, v115
	s_nop 0
	v_mul_f32_e32 v116, 0x45800000, v115
	v_cndmask_b32_e64 v130, v115, v116, s[2:3]
	ds_read_b64 v[116:117], v80 offset:128
	s_nop 0
	s_nop 0
	v_mul_f32_e32 v119, v130, v130
	v_ashrrev_i32_e32 v115, 31, v114
	v_lshlrev_b64 v[114:115], 8, v[114:115]
	s_waitcnt lgkmcnt(0)
; __device__ __forceinline__ unsigned cvt_pk_bf16(float lo, float hi) { unsigned r; asm("v_cvt_pk_bf16_f32 %0, %1, %2" : "=v"(r) : "v"(lo), "v"(hi)); return r; }
; __device__ __forceinline__ float rinv_of(unsigned long long ss) { return rsqrtf((float)ss * (1.f / 16777216.f) * (1.f / DM) + 1e-6f); }
;   __device__ __forceinline__ void operator()(const f32x4 (&acc)[2][2][4][2], const Unit& u, const EpiCtx& x_, int wr, int wc, int fr, int fq) const {
;     ...
;         const int t = u.r0 + ai * 128 + wr * 64 + m * 16 + fr;
;         const int seq = t / S, n = t % S, pos = seq * S + (n & ((1 << lg) - 1)) * L + (n >> lg);
;         const float rs = rinv_of(ssv[ai][m]);
;         const float* rp = (const float*)0; (void)rp;
;         const float r0 = red[((wr * 2 + hd) * 128 + ai * 64 + m * 16 + fr) * 2], r1 = red[((wr * 2 + hd) * 128 + ai * 64 + m * 16 + fr) * 2 + 1];
;         const float rinv = rs * rsqrtf((r0 + r1) * (rs * rs) * (1.f / 128.f) + 1e-6f);
; #pragma unroll
;         for (int bj = 0; bj < 2; ++bj) {
;           const f32x4 g0 = *(const f32x4*)(gbase + bj * 32), g1 = *(const f32x4*)(gbase + bj * 32 + 4);
;           const f32x4 v0 = acc[ai][bj][m][0] * rinv * g0, v1 = acc[ai][bj][m][1] * rinv * g1;
;           uint4 o; o.x = cvt_pk_bf16(v0[0], v0[1]); o.y = cvt_pk_bf16(v0[2], v0[3]); o.z = cvt_pk_bf16(v1[0], v1[1]); o.w = cvt_pk_bf16(v1[2], v1[3]);
;           *(uint4*)(obase + (size_t)pos * 128 + bj * 32) = o;
;         }
	v_pk_add_f32 v[116:117], v[116:117], v[116:117] op_sel_hi:[0,1]
	v_ffbh_u32_e32 v116, v159
	v_min_u32_e32 v116, 32, v116
	v_lshlrev_b64 v[128:129], v116, v[158:159]
	v_min_u32_e32 v118, 1, v128
	v_or_b32_e32 v118, v129, v118
	v_cvt_f32_u32_e32 v118, v118
	v_sub_u32_e32 v116, 32, v116
	v_mov_b32_e32 v181, v117
	v_lshl_add_u64 v[114:115], v[146:147], 0, v[114:115]
	v_ldexp_f32 v118, v118, v116
	v_pk_mul_f32 v[116:117], v[118:119], v[180:181]
	s_nop 0
	v_pk_fma_f32 v[116:117], v[116:117], s[26:27], v[150:151] op_sel_hi:[1,1,0]
	s_nop 0
	v_mul_f32_e32 v118, 0x4b800000, v117
	v_cmp_gt_f32_e64 s[4:5], s50, v117
	v_cmp_gt_f32_e64 s[2:3], s50, v116
	s_nop 0
	v_cndmask_b32_e64 v117, v117, v118, s[4:5]
	v_rsq_f32_e32 v117, v117
	s_nop 0
	v_mul_f32_e32 v118, 0x45800000, v117
	v_cndmask_b32_e64 v117, v117, v118, s[4:5]
	v_mul_f32_e32 v118, v130, v117
	v_pk_mul_f32 v[110:111], v[110:111], v[118:119] op_sel_hi:[1,0]
	v_pk_mul_f32 v[106:107], v[106:107], v[118:119] op_sel_hi:[1,0]
	v_pk_mul_f32 v[108:109], v[108:109], v[118:119] op_sel_hi:[1,0]
	v_pk_mul_f32 v[112:113], v[112:113], v[118:119] op_sel_hi:[1,0]
	v_pk_mul_f32 v[102:103], v[102:103], v[118:119] op_sel_hi:[1,0]
	v_pk_mul_f32 v[104:105], v[104:105], v[118:119] op_sel_hi:[1,0]
	v_pk_mul_f32 v[98:99], v[98:99], v[118:119] op_sel_hi:[1,0]
	v_pk_mul_f32 v[100:101], v[100:101], v[118:119] op_sel_hi:[1,0]
	s_nop 0
	v_pk_mul_f32 v[110:111], v[190:191], v[110:111]
	v_pk_mul_f32 v[120:121], v[196:197], v[108:109]
	v_pk_mul_f32 v[108:109], v[194:195], v[106:107]
	v_pk_mul_f32 v[112:113], v[192:193], v[112:113]
	v_cvt_pk_bf16_f32 v106, v110, v111
	v_cvt_pk_bf16_f32 v108, v108, v109
	v_cvt_pk_bf16_f32 v109, v120, v121
	s_nop 0
	v_cvt_pk_bf16_f32 v107, v112, v113
	global_store_dwordx4 v[114:115], v[106:109], off
	s_nop 0
	s_nop 0
	s_nop 0
	s_waitcnt lgkmcnt(0)
	v_pk_mul_f32 v[104:105], v[200:201], v[104:105]
	v_pk_mul_f32 v[102:103], v[198:199], v[102:103]
	v_pk_mul_f32 v[106:107], v[204:205], v[100:101]
	v_pk_mul_f32 v[100:101], v[202:203], v[98:99]
	v_cvt_pk_bf16_f32 v99, v104, v105
	v_cvt_pk_bf16_f32 v98, v102, v103
	s_nop 0
	v_cvt_pk_bf16_f32 v100, v100, v101
	v_cvt_pk_bf16_f32 v101, v106, v107
	global_store_dwordx4 v[114:115], v[98:101], off offset:64
	v_add_u32_e32 v115, s0, v171
	s_mov_b32 s0, s38
	s_ff1_i32_b32 s101, s17
	s_ff1_i32_b32 s100, s42
	v_bfe_u32 v98, v131, 0, s101
	v_bitop3_b32 v99, v98, s43, v98 bitop3:0x30
	v_lshlrev_b32_e32 v99, s100, v99
	v_ashrrev_i32_e32 v100, s39, v98
	v_sub_u32_e32 v98, v131, v98
	v_add3_u32 v98, v98, v100, v99
	v_mul_f32_e32 v99, 0x4b800000, v116
	v_cndmask_b32_e64 v99, v116, v99, s[2:3]
	v_rsq_f32_e32 v99, v99
	s_nop 0
	v_mul_f32_e32 v100, 0x45800000, v99
	v_cndmask_b32_e64 v114, v99, v100, s[2:3]
	ds_read_b64 v[100:101], v80 offset:256
	s_nop 0
	s_nop 0
	v_mul_f32_e32 v103, v114, v114
	v_ashrrev_i32_e32 v99, 31, v98
	v_lshlrev_b64 v[98:99], 8, v[98:99]
	s_waitcnt lgkmcnt(0)
	v_pk_add_f32 v[100:101], v[100:101], v[100:101] op_sel_hi:[0,1]
	v_ffbh_u32_e32 v100, v157
	v_min_u32_e32 v100, 32, v100
	v_lshlrev_b64 v[112:113], v100, v[156:157]
	v_min_u32_e32 v102, 1, v112
	v_or_b32_e32 v102, v113, v102
	v_cvt_f32_u32_e32 v102, v102
	v_sub_u32_e32 v100, 32, v100
	v_mov_b32_e32 v181, v101
	v_lshl_add_u64 v[98:99], v[146:147], 0, v[98:99]
	v_ldexp_f32 v102, v102, v100
	v_pk_mul_f32 v[100:101], v[102:103], v[180:181]
	s_nop 0
	v_pk_fma_f32 v[100:101], v[100:101], s[26:27], v[150:151] op_sel_hi:[1,1,0]
	s_nop 0
	v_mul_f32_e32 v102, 0x4b800000, v101
	v_cmp_gt_f32_e64 s[4:5], s50, v101
	v_cmp_gt_f32_e64 s[2:3], s50, v100
	s_nop 0
	v_cndmask_b32_e64 v101, v101, v102, s[4:5]
	v_rsq_f32_e32 v101, v101
	s_nop 0
	v_mul_f32_e32 v102, 0x45800000, v101
	v_cndmask_b32_e64 v101, v101, v102, s[4:5]
	v_mul_f32_e32 v102, v114, v101
	v_pk_mul_f32 v[94:95], v[94:95], v[102:103] op_sel_hi:[1,0]
	v_pk_mul_f32 v[90:91], v[90:91], v[102:103] op_sel_hi:[1,0]
	v_pk_mul_f32 v[92:93], v[92:93], v[102:103] op_sel_hi:[1,0]
	v_pk_mul_f32 v[96:97], v[96:97], v[102:103] op_sel_hi:[1,0]
	v_pk_mul_f32 v[86:87], v[86:87], v[102:103] op_sel_hi:[1,0]
	v_pk_mul_f32 v[88:89], v[88:89], v[102:103] op_sel_hi:[1,0]
	v_pk_mul_f32 v[82:83], v[82:83], v[102:103] op_sel_hi:[1,0]
	v_pk_mul_f32 v[84:85], v[84:85], v[102:103] op_sel_hi:[1,0]
	s_nop 0
	v_pk_mul_f32 v[94:95], v[190:191], v[94:95]
	v_pk_mul_f32 v[104:105], v[196:197], v[92:93]
	v_pk_mul_f32 v[92:93], v[194:195], v[90:91]
	v_pk_mul_f32 v[96:97], v[192:193], v[96:97]
	v_cvt_pk_bf16_f32 v90, v94, v95
	v_cvt_pk_bf16_f32 v92, v92, v93
	v_cvt_pk_bf16_f32 v93, v104, v105
	s_nop 0
	v_cvt_pk_bf16_f32 v91, v96, v97
	global_store_dwordx4 v[98:99], v[90:93], off
	s_nop 0
	s_nop 0
	s_nop 0
	s_waitcnt lgkmcnt(0)
	v_pk_mul_f32 v[88:89], v[200:201], v[88:89]
	v_pk_mul_f32 v[86:87], v[198:199], v[86:87]
	v_pk_mul_f32 v[90:91], v[204:205], v[84:85]
	v_pk_mul_f32 v[84:85], v[202:203], v[82:83]
	v_cvt_pk_bf16_f32 v83, v88, v89
	v_cvt_pk_bf16_f32 v82, v86, v87
	s_nop 0
	v_cvt_pk_bf16_f32 v84, v84, v85
	v_cvt_pk_bf16_f32 v85, v90, v91
	global_store_dwordx4 v[98:99], v[82:85], off offset:64
	v_add_u32_e32 v99, 0x80, v140
	s_nop 0
	s_ff1_i32_b32 s101, s17
	s_ff1_i32_b32 s100, s42
	v_bfe_u32 v82, v115, 0, s101
	v_bitop3_b32 v83, v82, s43, v82 bitop3:0x30
	v_lshlrev_b32_e32 v83, s100, v83
	v_ashrrev_i32_e32 v84, s39, v82
	v_sub_u32_e32 v82, v115, v82
	v_add3_u32 v82, v82, v84, v83
	v_mul_f32_e32 v83, 0x4b800000, v100
	v_cndmask_b32_e64 v83, v100, v83, s[2:3]
	v_rsq_f32_e32 v83, v83
	s_nop 0
	v_mul_f32_e32 v84, 0x45800000, v83
	v_cndmask_b32_e64 v98, v83, v84, s[2:3]
	ds_read_b64 v[84:85], v80 offset:384
	s_nop 0
	s_nop 0
	v_mul_f32_e32 v87, v98, v98
	v_ashrrev_i32_e32 v83, 31, v82
	v_lshlrev_b64 v[82:83], 8, v[82:83]
	s_waitcnt lgkmcnt(0)
; __device__ __forceinline__ unsigned cvt_pk_bf16(float lo, float hi) { unsigned r; asm("v_cvt_pk_bf16_f32 %0, %1, %2" : "=v"(r) : "v"(lo), "v"(hi)); return r; }
; __device__ __forceinline__ float rinv_of(unsigned long long ss) { return rsqrtf((float)ss * (1.f / 16777216.f) * (1.f / DM) + 1e-6f); }
;   __device__ __forceinline__ void operator()(const f32x4 (&acc)[2][2][4][2], const Unit& u, const EpiCtx& x_, int wr, int wc, int fr, int fq) const {
;     ...
;         const int t = u.r0 + ai * 128 + wr * 64 + m * 16 + fr;
;         const int seq = t / S, n = t % S, pos = seq * S + (n & ((1 << lg) - 1)) * L + (n >> lg);
;         const float rs = rinv_of(ssv[ai][m]);
;         const float* rp = (const float*)0; (void)rp;
;         const float r0 = red[((wr * 2 + hd) * 128 + ai * 64 + m * 16 + fr) * 2], r1 = red[((wr * 2 + hd) * 128 + ai * 64 + m * 16 + fr) * 2 + 1];
;         const float rinv = rs * rsqrtf((r0 + r1) * (rs * rs) * (1.f / 128.f) + 1e-6f);
; #pragma unroll
;         for (int bj = 0; bj < 2; ++bj) {
;           const f32x4 g0 = *(const f32x4*)(gbase + bj * 32), g1 = *(const f32x4*)(gbase + bj * 32 + 4);
;           const f32x4 v0 = acc[ai][bj][m][0] * rinv * g0, v1 = acc[ai][bj][m][1] * rinv * g1;
;           uint4 o; o.x = cvt_pk_bf16(v0[0], v0[1]); o.y = cvt_pk_bf16(v0[2], v0[3]); o.z = cvt_pk_bf16(v1[0], v1[1]); o.w = cvt_pk_bf16(v1[2], v1[3]);
;           *(uint4*)(obase + (size_t)pos * 128 + bj * 32) = o;
;         }
	v_pk_add_f32 v[84:85], v[84:85], v[84:85] op_sel_hi:[0,1]
	v_ffbh_u32_e32 v84, v155
	v_min_u32_e32 v84, 32, v84
	v_lshlrev_b64 v[96:97], v84, v[154:155]
	v_min_u32_e32 v86, 1, v96
	v_or_b32_e32 v86, v97, v86
	v_cvt_f32_u32_e32 v86, v86
	v_sub_u32_e32 v84, 32, v84
	v_mov_b32_e32 v181, v85
	v_lshl_add_u64 v[82:83], v[146:147], 0, v[82:83]
	v_ldexp_f32 v86, v86, v84
	v_pk_mul_f32 v[84:85], v[86:87], v[180:181]
	s_nop 0
	v_pk_fma_f32 v[84:85], v[84:85], s[26:27], v[150:151] op_sel_hi:[1,1,0]
	s_nop 0
	v_mul_f32_e32 v86, 0x4b800000, v85
	v_cmp_gt_f32_e64 s[4:5], s50, v85
	v_cmp_gt_f32_e64 s[2:3], s50, v84
	s_nop 0
	v_cndmask_b32_e64 v85, v85, v86, s[4:5]
	v_rsq_f32_e32 v85, v85
	s_nop 0
	v_mul_f32_e32 v86, 0x45800000, v85
	v_cndmask_b32_e64 v85, v85, v86, s[4:5]
	v_mul_f32_e32 v86, v98, v85
	v_pk_mul_f32 v[76:77], v[76:77], v[86:87] op_sel_hi:[1,0]
	v_pk_mul_f32 v[72:73], v[72:73], v[86:87] op_sel_hi:[1,0]
	v_pk_mul_f32 v[74:75], v[74:75], v[86:87] op_sel_hi:[1,0]
	v_pk_mul_f32 v[78:79], v[78:79], v[86:87] op_sel_hi:[1,0]
	v_pk_mul_f32 v[68:69], v[68:69], v[86:87] op_sel_hi:[1,0]
	v_pk_mul_f32 v[70:71], v[70:71], v[86:87] op_sel_hi:[1,0]
	v_pk_mul_f32 v[64:65], v[64:65], v[86:87] op_sel_hi:[1,0]
	v_pk_mul_f32 v[66:67], v[66:67], v[86:87] op_sel_hi:[1,0]
	s_nop 0
	v_pk_mul_f32 v[76:77], v[190:191], v[76:77]
	v_pk_mul_f32 v[88:89], v[196:197], v[74:75]
	v_pk_mul_f32 v[74:75], v[194:195], v[72:73]
	v_pk_mul_f32 v[78:79], v[192:193], v[78:79]
	v_cvt_pk_bf16_f32 v72, v76, v77
	v_cvt_pk_bf16_f32 v74, v74, v75
	v_cvt_pk_bf16_f32 v75, v88, v89
	s_nop 0
	v_cvt_pk_bf16_f32 v73, v78, v79
	global_store_dwordx4 v[82:83], v[72:75], off
	s_nop 0
	s_nop 0
	s_nop 0
	s_waitcnt lgkmcnt(0)
	v_pk_mul_f32 v[70:71], v[200:201], v[70:71]
	v_pk_mul_f32 v[68:69], v[198:199], v[68:69]
	v_pk_mul_f32 v[72:73], v[204:205], v[66:67]
	v_pk_mul_f32 v[66:67], v[202:203], v[64:65]
	v_cvt_pk_bf16_f32 v65, v70, v71
	v_cvt_pk_bf16_f32 v64, v68, v69
	s_nop 0
	v_cvt_pk_bf16_f32 v66, v66, v67
	v_cvt_pk_bf16_f32 v67, v72, v73
	global_store_dwordx4 v[82:83], v[64:67], off offset:64
	v_add_u32_e32 v83, 0x90, v140
	s_nop 0
	s_ff1_i32_b32 s101, s17
	s_ff1_i32_b32 s100, s42
	v_bfe_u32 v64, v99, 0, s101
	v_bitop3_b32 v65, v64, s43, v64 bitop3:0x30
	v_lshlrev_b32_e32 v65, s100, v65
	v_ashrrev_i32_e32 v66, s39, v64
	v_sub_u32_e32 v64, v99, v64
	v_add3_u32 v64, v64, v66, v65
	v_mul_f32_e32 v65, 0x4b800000, v84
	v_cndmask_b32_e64 v65, v84, v65, s[2:3]
	v_rsq_f32_e32 v65, v65
	s_nop 0
	v_mul_f32_e32 v66, 0x45800000, v65
	v_cndmask_b32_e64 v82, v65, v66, s[2:3]
	ds_read_b64 v[66:67], v80 offset:512
	s_nop 0
	s_nop 0
	v_mul_f32_e32 v69, v82, v82
	v_ashrrev_i32_e32 v65, 31, v64
	v_lshlrev_b64 v[64:65], 8, v[64:65]
	s_waitcnt lgkmcnt(0)
	v_pk_add_f32 v[66:67], v[66:67], v[66:67] op_sel_hi:[0,1]
	v_ffbh_u32_e32 v66, v153
	v_min_u32_e32 v66, 32, v66
	v_lshlrev_b64 v[78:79], v66, v[152:153]
	v_min_u32_e32 v68, 1, v78
	v_or_b32_e32 v68, v79, v68
	v_cvt_f32_u32_e32 v68, v68
	v_sub_u32_e32 v66, 32, v66
	v_mov_b32_e32 v181, v67
	v_lshl_add_u64 v[64:65], v[146:147], 0, v[64:65]
	v_ldexp_f32 v68, v68, v66
	v_pk_mul_f32 v[66:67], v[68:69], v[180:181]
	s_nop 0
	v_pk_fma_f32 v[66:67], v[66:67], s[26:27], v[150:151] op_sel_hi:[1,1,0]
	s_nop 0
	v_mul_f32_e32 v68, 0x4b800000, v67
	v_cmp_gt_f32_e64 s[4:5], s50, v67
	v_cmp_gt_f32_e64 s[2:3], s50, v66
	s_nop 0
	v_cndmask_b32_e64 v67, v67, v68, s[4:5]
	v_rsq_f32_e32 v67, v67
	s_nop 0
	v_mul_f32_e32 v68, 0x45800000, v67
	v_cndmask_b32_e64 v67, v67, v68, s[4:5]
	v_mul_f32_e32 v68, v82, v67
	v_pk_mul_f32 v[60:61], v[60:61], v[68:69] op_sel_hi:[1,0]
	v_pk_mul_f32 v[56:57], v[56:57], v[68:69] op_sel_hi:[1,0]
	v_pk_mul_f32 v[58:59], v[58:59], v[68:69] op_sel_hi:[1,0]
	v_pk_mul_f32 v[62:63], v[62:63], v[68:69] op_sel_hi:[1,0]
	v_pk_mul_f32 v[52:53], v[52:53], v[68:69] op_sel_hi:[1,0]
	v_pk_mul_f32 v[54:55], v[54:55], v[68:69] op_sel_hi:[1,0]
	v_pk_mul_f32 v[48:49], v[48:49], v[68:69] op_sel_hi:[1,0]
	v_pk_mul_f32 v[50:51], v[50:51], v[68:69] op_sel_hi:[1,0]
	s_nop 0
	v_pk_mul_f32 v[60:61], v[190:191], v[60:61]
	v_pk_mul_f32 v[70:71], v[196:197], v[58:59]
	v_pk_mul_f32 v[58:59], v[194:195], v[56:57]
	v_pk_mul_f32 v[62:63], v[192:193], v[62:63]
	v_cvt_pk_bf16_f32 v56, v60, v61
	v_cvt_pk_bf16_f32 v58, v58, v59
	v_cvt_pk_bf16_f32 v59, v70, v71
	s_nop 0
	v_cvt_pk_bf16_f32 v57, v62, v63
	global_store_dwordx4 v[64:65], v[56:59], off
	s_nop 0
	s_nop 0
	s_nop 0
	s_waitcnt lgkmcnt(0)
	v_pk_mul_f32 v[54:55], v[200:201], v[54:55]
	v_pk_mul_f32 v[52:53], v[198:199], v[52:53]
	v_pk_mul_f32 v[56:57], v[204:205], v[50:51]
	v_pk_mul_f32 v[50:51], v[202:203], v[48:49]
	v_cvt_pk_bf16_f32 v49, v54, v55
	v_cvt_pk_bf16_f32 v48, v52, v53
	s_nop 0
	v_cvt_pk_bf16_f32 v50, v50, v51
	v_cvt_pk_bf16_f32 v51, v56, v57
	global_store_dwordx4 v[64:65], v[48:51], off offset:64
	v_add_u32_e32 v65, 0xa0, v140
	s_nop 0
	s_ff1_i32_b32 s101, s17
	s_ff1_i32_b32 s100, s42
	v_bfe_u32 v48, v83, 0, s101
	v_bitop3_b32 v49, v48, s43, v48 bitop3:0x30
	v_lshlrev_b32_e32 v49, s100, v49
	v_ashrrev_i32_e32 v50, s39, v48
	v_sub_u32_e32 v48, v83, v48
	v_add3_u32 v48, v48, v50, v49
	v_mul_f32_e32 v49, 0x4b800000, v66
	v_cndmask_b32_e64 v49, v66, v49, s[2:3]
	v_rsq_f32_e32 v49, v49
	s_nop 0
	v_mul_f32_e32 v50, 0x45800000, v49
	v_cndmask_b32_e64 v64, v49, v50, s[2:3]
	ds_read_b64 v[50:51], v80 offset:640
	s_nop 0
	s_nop 0
	v_mul_f32_e32 v53, v64, v64
	v_ashrrev_i32_e32 v49, 31, v48
	v_lshlrev_b64 v[48:49], 8, v[48:49]
	s_waitcnt lgkmcnt(0)
; __device__ __forceinline__ unsigned cvt_pk_bf16(float lo, float hi) { unsigned r; asm("v_cvt_pk_bf16_f32 %0, %1, %2" : "=v"(r) : "v"(lo), "v"(hi)); return r; }
; __device__ __forceinline__ float rinv_of(unsigned long long ss) { return rsqrtf((float)ss * (1.f / 16777216.f) * (1.f / DM) + 1e-6f); }
;   __device__ __forceinline__ void operator()(const f32x4 (&acc)[2][2][4][2], const Unit& u, const EpiCtx& x_, int wr, int wc, int fr, int fq) const {
;     ...
;         const int t = u.r0 + ai * 128 + wr * 64 + m * 16 + fr;
;         const int seq = t / S, n = t % S, pos = seq * S + (n & ((1 << lg) - 1)) * L + (n >> lg);
;         const float rs = rinv_of(ssv[ai][m]);
;         const float* rp = (const float*)0; (void)rp;
;         const float r0 = red[((wr * 2 + hd) * 128 + ai * 64 + m * 16 + fr) * 2], r1 = red[((wr * 2 + hd) * 128 + ai * 64 + m * 16 + fr) * 2 + 1];
;         const float rinv = rs * rsqrtf((r0 + r1) * (rs * rs) * (1.f / 128.f) + 1e-6f);
; #pragma unroll
;         for (int bj = 0; bj < 2; ++bj) {
;           const f32x4 g0 = *(const f32x4*)(gbase + bj * 32), g1 = *(const f32x4*)(gbase + bj * 32 + 4);
;           const f32x4 v0 = acc[ai][bj][m][0] * rinv * g0, v1 = acc[ai][bj][m][1] * rinv * g1;
;           uint4 o; o.x = cvt_pk_bf16(v0[0], v0[1]); o.y = cvt_pk_bf16(v0[2], v0[3]); o.z = cvt_pk_bf16(v1[0], v1[1]); o.w = cvt_pk_bf16(v1[2], v1[3]);
;           *(uint4*)(obase + (size_t)pos * 128 + bj * 32) = o;
;         }
	v_pk_add_f32 v[50:51], v[50:51], v[50:51] op_sel_hi:[0,1]
	v_ffbh_u32_e32 v50, v149
	v_min_u32_e32 v50, 32, v50
	v_lshlrev_b64 v[62:63], v50, v[148:149]
	v_min_u32_e32 v52, 1, v62
	v_or_b32_e32 v52, v63, v52
	v_cvt_f32_u32_e32 v52, v52
	v_sub_u32_e32 v50, 32, v50
	v_mov_b32_e32 v181, v51
	v_lshl_add_u64 v[48:49], v[146:147], 0, v[48:49]
	v_ldexp_f32 v52, v52, v50
	v_pk_mul_f32 v[50:51], v[52:53], v[180:181]
	s_nop 0
	v_pk_fma_f32 v[50:51], v[50:51], s[26:27], v[150:151] op_sel_hi:[1,1,0]
	s_nop 0
	v_mul_f32_e32 v52, 0x4b800000, v51
	v_cmp_gt_f32_e64 s[4:5], s50, v51
	v_cmp_gt_f32_e64 s[2:3], s50, v50
	s_nop 0
	v_cndmask_b32_e64 v51, v51, v52, s[4:5]
	v_rsq_f32_e32 v51, v51
	s_nop 0
	v_mul_f32_e32 v52, 0x45800000, v51
	v_cndmask_b32_e64 v51, v51, v52, s[4:5]
	v_mul_f32_e32 v52, v64, v51
	v_pk_mul_f32 v[44:45], v[44:45], v[52:53] op_sel_hi:[1,0]
	v_pk_mul_f32 v[40:41], v[40:41], v[52:53] op_sel_hi:[1,0]
	v_pk_mul_f32 v[42:43], v[42:43], v[52:53] op_sel_hi:[1,0]
	v_pk_mul_f32 v[46:47], v[46:47], v[52:53] op_sel_hi:[1,0]
	v_pk_mul_f32 v[36:37], v[36:37], v[52:53] op_sel_hi:[1,0]
	v_pk_mul_f32 v[38:39], v[38:39], v[52:53] op_sel_hi:[1,0]
	v_pk_mul_f32 v[32:33], v[32:33], v[52:53] op_sel_hi:[1,0]
	v_pk_mul_f32 v[34:35], v[34:35], v[52:53] op_sel_hi:[1,0]
	s_nop 0
	v_pk_mul_f32 v[44:45], v[190:191], v[44:45]
	v_pk_mul_f32 v[54:55], v[196:197], v[42:43]
	v_pk_mul_f32 v[42:43], v[194:195], v[40:41]
	v_pk_mul_f32 v[46:47], v[192:193], v[46:47]
	v_cvt_pk_bf16_f32 v40, v44, v45
	v_cvt_pk_bf16_f32 v42, v42, v43
	v_cvt_pk_bf16_f32 v43, v54, v55
	s_nop 0
	v_cvt_pk_bf16_f32 v41, v46, v47
	global_store_dwordx4 v[48:49], v[40:43], off
	s_nop 0
	s_nop 0
	s_nop 0
	s_waitcnt lgkmcnt(0)
	v_pk_mul_f32 v[38:39], v[200:201], v[38:39]
	v_pk_mul_f32 v[36:37], v[198:199], v[36:37]
	v_pk_mul_f32 v[40:41], v[204:205], v[34:35]
	v_pk_mul_f32 v[34:35], v[202:203], v[32:33]
	v_cvt_pk_bf16_f32 v33, v38, v39
	v_cvt_pk_bf16_f32 v32, v36, v37
	s_nop 0
	v_cvt_pk_bf16_f32 v34, v34, v35
	v_cvt_pk_bf16_f32 v35, v40, v41
	global_store_dwordx4 v[48:49], v[32:35], off offset:64
	v_add_u32_e32 v49, 0xb0, v140
	s_nop 0
	s_ff1_i32_b32 s101, s17
	s_ff1_i32_b32 s100, s42
	v_bfe_u32 v32, v65, 0, s101
	v_bitop3_b32 v33, v32, s43, v32 bitop3:0x30
	v_lshlrev_b32_e32 v33, s100, v33
	v_ashrrev_i32_e32 v34, s39, v32
	v_sub_u32_e32 v32, v65, v32
	v_add3_u32 v32, v32, v34, v33
	v_mul_f32_e32 v33, 0x4b800000, v50
	v_cndmask_b32_e64 v33, v50, v33, s[2:3]
	v_rsq_f32_e32 v33, v33
	s_nop 0
	v_mul_f32_e32 v34, 0x45800000, v33
	v_cndmask_b32_e64 v48, v33, v34, s[2:3]
	ds_read_b64 v[34:35], v80 offset:768
	s_nop 0
	s_nop 0
	v_mul_f32_e32 v37, v48, v48
	v_ashrrev_i32_e32 v33, 31, v32
	v_lshlrev_b64 v[32:33], 8, v[32:33]
	s_waitcnt lgkmcnt(0)
; __device__ __forceinline__ unsigned cvt_pk_bf16(float lo, float hi) { unsigned r; asm("v_cvt_pk_bf16_f32 %0, %1, %2" : "=v"(r) : "v"(lo), "v"(hi)); return r; }
; __device__ __forceinline__ float rinv_of(unsigned long long ss) { return rsqrtf((float)ss * (1.f / 16777216.f) * (1.f / DM) + 1e-6f); }
;   __device__ __forceinline__ void operator()(const f32x4 (&acc)[2][2][4][2], const Unit& u, const EpiCtx& x_, int wr, int wc, int fr, int fq) const {
;     ...
;         const int t = u.r0 + ai * 128 + wr * 64 + m * 16 + fr;
;         const int seq = t / S, n = t % S, pos = seq * S + (n & ((1 << lg) - 1)) * L + (n >> lg);
;         const float rs = rinv_of(ssv[ai][m]);
;         const float* rp = (const float*)0; (void)rp;
;         const float r0 = red[((wr * 2 + hd) * 128 + ai * 64 + m * 16 + fr) * 2], r1 = red[((wr * 2 + hd) * 128 + ai * 64 + m * 16 + fr) * 2 + 1];
;         const float rinv = rs * rsqrtf((r0 + r1) * (rs * rs) * (1.f / 128.f) + 1e-6f);
; #pragma unroll
;         for (int bj = 0; bj < 2; ++bj) {
;           const f32x4 g0 = *(const f32x4*)(gbase + bj * 32), g1 = *(const f32x4*)(gbase + bj * 32 + 4);
;           const f32x4 v0 = acc[ai][bj][m][0] * rinv * g0, v1 = acc[ai][bj][m][1] * rinv * g1;
;           uint4 o; o.x = cvt_pk_bf16(v0[0], v0[1]); o.y = cvt_pk_bf16(v0[2], v0[3]); o.z = cvt_pk_bf16(v1[0], v1[1]); o.w = cvt_pk_bf16(v1[2], v1[3]);
;           *(uint4*)(obase + (size_t)pos * 128 + bj * 32) = o;
;         }
	v_pk_add_f32 v[34:35], v[34:35], v[34:35] op_sel_hi:[0,1]
	v_ffbh_u32_e32 v34, v145
	v_min_u32_e32 v34, 32, v34
	v_lshlrev_b64 v[46:47], v34, v[144:145]
	v_min_u32_e32 v36, 1, v46
	v_or_b32_e32 v36, v47, v36
	v_cvt_f32_u32_e32 v36, v36
	v_sub_u32_e32 v34, 32, v34
	v_mov_b32_e32 v181, v35
	v_lshl_add_u64 v[32:33], v[146:147], 0, v[32:33]
	v_ldexp_f32 v36, v36, v34
	v_pk_mul_f32 v[34:35], v[36:37], v[180:181]
	s_nop 0
	v_pk_fma_f32 v[34:35], v[34:35], s[26:27], v[150:151] op_sel_hi:[1,1,0]
	s_nop 0
	v_mul_f32_e32 v36, 0x4b800000, v35
	v_cmp_gt_f32_e64 s[4:5], s50, v35
	v_cmp_gt_f32_e64 s[2:3], s50, v34
	s_nop 0
	v_cndmask_b32_e64 v35, v35, v36, s[4:5]
	v_rsq_f32_e32 v35, v35
	s_nop 0
	v_mul_f32_e32 v36, 0x45800000, v35
	v_cndmask_b32_e64 v35, v35, v36, s[4:5]
	v_mul_f32_e32 v36, v48, v35
	v_pk_mul_f32 v[28:29], v[28:29], v[36:37] op_sel_hi:[1,0]
	v_pk_mul_f32 v[24:25], v[24:25], v[36:37] op_sel_hi:[1,0]
	v_pk_mul_f32 v[26:27], v[26:27], v[36:37] op_sel_hi:[1,0]
	v_pk_mul_f32 v[30:31], v[30:31], v[36:37] op_sel_hi:[1,0]
	v_pk_mul_f32 v[20:21], v[20:21], v[36:37] op_sel_hi:[1,0]
	v_pk_mul_f32 v[22:23], v[22:23], v[36:37] op_sel_hi:[1,0]
	v_pk_mul_f32 v[16:17], v[16:17], v[36:37] op_sel_hi:[1,0]
	v_pk_mul_f32 v[18:19], v[18:19], v[36:37] op_sel_hi:[1,0]
	s_nop 0
	v_pk_mul_f32 v[28:29], v[190:191], v[28:29]
	v_pk_mul_f32 v[38:39], v[196:197], v[26:27]
	v_pk_mul_f32 v[26:27], v[194:195], v[24:25]
	v_pk_mul_f32 v[30:31], v[192:193], v[30:31]
	v_cvt_pk_bf16_f32 v24, v28, v29
	v_cvt_pk_bf16_f32 v26, v26, v27
	v_cvt_pk_bf16_f32 v27, v38, v39
	s_nop 0
	v_cvt_pk_bf16_f32 v25, v30, v31
	global_store_dwordx4 v[32:33], v[24:27], off
	s_nop 0
	s_nop 0
	s_nop 0
	s_waitcnt lgkmcnt(0)
	v_pk_mul_f32 v[22:23], v[200:201], v[22:23]
	v_pk_mul_f32 v[20:21], v[198:199], v[20:21]
	v_pk_mul_f32 v[24:25], v[204:205], v[18:19]
	v_pk_mul_f32 v[18:19], v[202:203], v[16:17]
	v_cvt_pk_bf16_f32 v17, v22, v23
	v_cvt_pk_bf16_f32 v16, v20, v21
	s_nop 0
	v_cvt_pk_bf16_f32 v18, v18, v19
	v_cvt_pk_bf16_f32 v19, v24, v25
	global_store_dwordx4 v[32:33], v[16:19], off offset:64
	s_nop 1
	s_ff1_i32_b32 s101, s17
	s_ff1_i32_b32 s100, s42
	v_bfe_u32 v16, v49, 0, s101
	v_bitop3_b32 v17, v16, s43, v16 bitop3:0x30
	v_lshlrev_b32_e32 v17, s100, v17
	v_ashrrev_i32_e32 v18, s39, v16
	v_sub_u32_e32 v16, v49, v16
	v_add3_u32 v16, v16, v18, v17
	v_mul_f32_e32 v17, 0x4b800000, v34
	v_cndmask_b32_e64 v17, v34, v17, s[2:3]
	v_rsq_f32_e32 v17, v17
	s_mov_b64 s[4:5], s[94:95]
	v_mul_f32_e32 v18, 0x45800000, v17
	v_cndmask_b32_e64 v17, v17, v18, s[2:3]
	ds_read_b64 v[18:19], v80 offset:896
	s_nop 0
	s_nop 0
	s_waitcnt lgkmcnt(0)
	v_add_f32_e32 v18, v18, v19
	v_mul_f32_e32 v19, v17, v17
	v_mul_f32_e32 v18, v19, v18
	v_fmamk_f32 v18, v18, 0x3c000000, v234
	v_cmp_gt_f32_e64 s[2:3], s50, v18
	v_mul_f32_e32 v19, 0x4b800000, v18
	s_nop 0
	v_cndmask_b32_e64 v18, v18, v19, s[2:3]
	v_rsq_f32_e32 v18, v18
	s_nop 0
	v_mul_f32_e32 v19, 0x45800000, v18
	v_cndmask_b32_e64 v18, v18, v19, s[2:3]
	v_mul_f32_e32 v18, v17, v18
	v_ashrrev_i32_e32 v17, 31, v16
	v_lshlrev_b64 v[16:17], 8, v[16:17]
	v_pk_mul_f32 v[12:13], v[12:13], v[18:19] op_sel_hi:[1,0]
	v_pk_mul_f32 v[8:9], v[8:9], v[18:19] op_sel_hi:[1,0]
	v_pk_mul_f32 v[10:11], v[10:11], v[18:19] op_sel_hi:[1,0]
	v_lshl_add_u64 v[16:17], v[146:147], 0, v[16:17]
	v_pk_mul_f32 v[14:15], v[14:15], v[18:19] op_sel_hi:[1,0]
	v_pk_mul_f32 v[4:5], v[4:5], v[18:19] op_sel_hi:[1,0]
	v_pk_mul_f32 v[0:1], v[0:1], v[18:19] op_sel_hi:[1,0]
	v_pk_mul_f32 v[2:3], v[2:3], v[18:19] op_sel_hi:[1,0]
	v_pk_mul_f32 v[6:7], v[6:7], v[18:19] op_sel_hi:[1,0]
	s_nop 0
	v_pk_mul_f32 v[12:13], v[190:191], v[12:13]
	v_pk_mul_f32 v[20:21], v[196:197], v[10:11]
	v_pk_mul_f32 v[10:11], v[194:195], v[8:9]
	v_pk_mul_f32 v[14:15], v[192:193], v[14:15]
	v_cvt_pk_bf16_f32 v8, v12, v13
	v_cvt_pk_bf16_f32 v10, v10, v11
	v_cvt_pk_bf16_f32 v11, v20, v21
	s_nop 0
	v_cvt_pk_bf16_f32 v9, v14, v15
	global_store_dwordx4 v[16:17], v[8:11], off
	s_nop 0
	s_nop 0
	s_nop 0
	s_waitcnt lgkmcnt(0)
	v_pk_mul_f32 v[4:5], v[198:199], v[4:5]
	v_pk_mul_f32 v[8:9], v[204:205], v[2:3]
	v_pk_mul_f32 v[2:3], v[202:203], v[0:1]
	v_pk_mul_f32 v[6:7], v[200:201], v[6:7]
	v_cvt_pk_bf16_f32 v0, v4, v5
	v_cvt_pk_bf16_f32 v2, v2, v3
	v_cvt_pk_bf16_f32 v3, v8, v9
	s_nop 0
	v_cvt_pk_bf16_f32 v1, v6, v7
	global_store_dwordx4 v[16:17], v[0:3], off offset:64
	s_cbranch_scc1 .LBB0_606
